# hand-written rms-norm row code for the three bf16 norm phases: 16-byte accesses, 4 rows in flight, scale/shift read once per chunk
# speedup vs baseline: 1.0199x; 1.0057x over previous
.LBB0_834:
	s_or_b64 exec, exec, s[18:19]
	v_and_b32_e32 v10, 63, v0
	v_lshlrev_b32_e32 v62, 5, v10
	v_lshlrev_b32_e32 v11, 3, v10
	v_add_u32_e32 v12, s36, v1
	v_lshl_add_u32 v12, v12, 11, v11
	v_mov_b32_e32 v13, 0
	v_lshl_add_u64 v[14:15], v[12:13], 0, v[20:21]
	v_lshl_add_u64 v[16:17], v[12:13], 0, v[22:23]
	v_add_u32_e32 v12, 0x1000, v12
	v_lshl_add_u64 v[8:9], v[12:13], 0, v[20:21]
	v_lshl_add_u64 v[10:11], v[12:13], 0, v[22:23]
	global_load_dwordx4 v[64:67], v[14:15], off
	global_load_dwordx4 v[68:71], v[14:15], off offset:1024
	global_load_dwordx4 v[72:75], v[14:15], off offset:2048
	global_load_dwordx4 v[76:79], v[14:15], off offset:3072
	global_load_dwordx4 v[80:83], v[8:9], off
	global_load_dwordx4 v[84:87], v[8:9], off offset:1024
	global_load_dwordx4 v[88:91], v[8:9], off offset:2048
	global_load_dwordx4 v[92:95], v[8:9], off offset:3072
	s_waitcnt lgkmcnt(0)
	s_barrier
	ds_read_b128 v[96:99], v62 offset:4096
	ds_read_b128 v[100:103], v62 offset:4112
	ds_read_b128 v[104:107], v62 offset:6144
	ds_read_b128 v[108:111], v62 offset:6160
	ds_read_b128 v[112:115], v62
	ds_read_b128 v[116:119], v62 offset:16
	ds_read_b128 v[40:43], v62 offset:2048
	ds_read_b128 v[44:47], v62 offset:2064
	s_waitcnt vmcnt(6)
	v_lshlrev_b32_e32 v26, 16, v64
	v_and_b32_e32 v27, 0xffff0000, v64
	v_mul_f32_e32 v4, v26, v26
	v_mul_f32_e32 v2, v27, v27
	v_lshlrev_b32_e32 v26, 16, v65
	v_and_b32_e32 v27, 0xffff0000, v65
	v_fmac_f32_e32 v4, v26, v26
	v_fmac_f32_e32 v2, v27, v27
	v_lshlrev_b32_e32 v26, 16, v66
	v_and_b32_e32 v27, 0xffff0000, v66
	v_fmac_f32_e32 v4, v26, v26
	v_fmac_f32_e32 v2, v27, v27
	v_lshlrev_b32_e32 v26, 16, v67
	v_and_b32_e32 v27, 0xffff0000, v67
	v_fmac_f32_e32 v4, v26, v26
	v_fmac_f32_e32 v2, v27, v27
	v_lshlrev_b32_e32 v26, 16, v68
	v_and_b32_e32 v27, 0xffff0000, v68
	v_fmac_f32_e32 v4, v26, v26
	v_fmac_f32_e32 v2, v27, v27
	v_lshlrev_b32_e32 v26, 16, v69
	v_and_b32_e32 v27, 0xffff0000, v69
	v_fmac_f32_e32 v4, v26, v26
	v_fmac_f32_e32 v2, v27, v27
	v_lshlrev_b32_e32 v26, 16, v70
	v_and_b32_e32 v27, 0xffff0000, v70
	v_fmac_f32_e32 v4, v26, v26
	v_fmac_f32_e32 v2, v27, v27
	v_lshlrev_b32_e32 v26, 16, v71
	v_and_b32_e32 v27, 0xffff0000, v71
	v_fmac_f32_e32 v4, v26, v26
	v_fmac_f32_e32 v2, v27, v27
	v_add_f32_e32 v4, v4, v2
	s_waitcnt vmcnt(4)
	v_lshlrev_b32_e32 v26, 16, v72
	v_and_b32_e32 v27, 0xffff0000, v72
	v_mul_f32_e32 v5, v26, v26
	v_mul_f32_e32 v3, v27, v27
	v_lshlrev_b32_e32 v26, 16, v73
	v_and_b32_e32 v27, 0xffff0000, v73
	v_fmac_f32_e32 v5, v26, v26
	v_fmac_f32_e32 v3, v27, v27
	v_lshlrev_b32_e32 v26, 16, v74
	v_and_b32_e32 v27, 0xffff0000, v74
	v_fmac_f32_e32 v5, v26, v26
	v_fmac_f32_e32 v3, v27, v27
	v_lshlrev_b32_e32 v26, 16, v75
	v_and_b32_e32 v27, 0xffff0000, v75
	v_fmac_f32_e32 v5, v26, v26
	v_fmac_f32_e32 v3, v27, v27
	v_lshlrev_b32_e32 v26, 16, v76
	v_and_b32_e32 v27, 0xffff0000, v76
	v_fmac_f32_e32 v5, v26, v26
	v_fmac_f32_e32 v3, v27, v27
	v_lshlrev_b32_e32 v26, 16, v77
	v_and_b32_e32 v27, 0xffff0000, v77
	v_fmac_f32_e32 v5, v26, v26
	v_fmac_f32_e32 v3, v27, v27
	v_lshlrev_b32_e32 v26, 16, v78
	v_and_b32_e32 v27, 0xffff0000, v78
	v_fmac_f32_e32 v5, v26, v26
	v_fmac_f32_e32 v3, v27, v27
	v_lshlrev_b32_e32 v26, 16, v79
	v_and_b32_e32 v27, 0xffff0000, v79
	v_fmac_f32_e32 v5, v26, v26
	v_fmac_f32_e32 v3, v27, v27
	v_add_f32_e32 v5, v5, v3
	s_waitcnt vmcnt(2)
	v_lshlrev_b32_e32 v26, 16, v80
	v_and_b32_e32 v27, 0xffff0000, v80
	v_mul_f32_e32 v6, v26, v26
	v_mul_f32_e32 v24, v27, v27
	v_lshlrev_b32_e32 v26, 16, v81
	v_and_b32_e32 v27, 0xffff0000, v81
	v_fmac_f32_e32 v6, v26, v26
	v_fmac_f32_e32 v24, v27, v27
	v_lshlrev_b32_e32 v26, 16, v82
	v_and_b32_e32 v27, 0xffff0000, v82
	v_fmac_f32_e32 v6, v26, v26
	v_fmac_f32_e32 v24, v27, v27
	v_lshlrev_b32_e32 v26, 16, v83
	v_and_b32_e32 v27, 0xffff0000, v83
	v_fmac_f32_e32 v6, v26, v26
	v_fmac_f32_e32 v24, v27, v27
	v_lshlrev_b32_e32 v26, 16, v84
	v_and_b32_e32 v27, 0xffff0000, v84
	v_fmac_f32_e32 v6, v26, v26
	v_fmac_f32_e32 v24, v27, v27
	v_lshlrev_b32_e32 v26, 16, v85
	v_and_b32_e32 v27, 0xffff0000, v85
	v_fmac_f32_e32 v6, v26, v26
	v_fmac_f32_e32 v24, v27, v27
	v_lshlrev_b32_e32 v26, 16, v86
	v_and_b32_e32 v27, 0xffff0000, v86
	v_fmac_f32_e32 v6, v26, v26
	v_fmac_f32_e32 v24, v27, v27
	v_lshlrev_b32_e32 v26, 16, v87
	v_and_b32_e32 v27, 0xffff0000, v87
	v_fmac_f32_e32 v6, v26, v26
	v_fmac_f32_e32 v24, v27, v27
	v_add_f32_e32 v6, v6, v24
	s_waitcnt vmcnt(0)
	v_lshlrev_b32_e32 v26, 16, v88
	v_and_b32_e32 v27, 0xffff0000, v88
	v_mul_f32_e32 v7, v26, v26
	v_mul_f32_e32 v25, v27, v27
	v_lshlrev_b32_e32 v26, 16, v89
	v_and_b32_e32 v27, 0xffff0000, v89
	v_fmac_f32_e32 v7, v26, v26
	v_fmac_f32_e32 v25, v27, v27
	v_lshlrev_b32_e32 v26, 16, v90
	v_and_b32_e32 v27, 0xffff0000, v90
	v_fmac_f32_e32 v7, v26, v26
	v_fmac_f32_e32 v25, v27, v27
	v_lshlrev_b32_e32 v26, 16, v91
	v_and_b32_e32 v27, 0xffff0000, v91
	v_fmac_f32_e32 v7, v26, v26
	v_fmac_f32_e32 v25, v27, v27
	v_lshlrev_b32_e32 v26, 16, v92
	v_and_b32_e32 v27, 0xffff0000, v92
	v_fmac_f32_e32 v7, v26, v26
	v_fmac_f32_e32 v25, v27, v27
	v_lshlrev_b32_e32 v26, 16, v93
	v_and_b32_e32 v27, 0xffff0000, v93
	v_fmac_f32_e32 v7, v26, v26
	v_fmac_f32_e32 v25, v27, v27
	v_lshlrev_b32_e32 v26, 16, v94
	v_and_b32_e32 v27, 0xffff0000, v94
	v_fmac_f32_e32 v7, v26, v26
	v_fmac_f32_e32 v25, v27, v27
	v_lshlrev_b32_e32 v26, 16, v95
	v_and_b32_e32 v27, 0xffff0000, v95
	v_fmac_f32_e32 v7, v26, v26
	v_fmac_f32_e32 v25, v27, v27
	v_add_f32_e32 v7, v7, v25
	ds_bpermute_b32 v28, v50, v4
	ds_bpermute_b32 v29, v50, v5
	ds_bpermute_b32 v30, v50, v6
	ds_bpermute_b32 v31, v50, v7
	s_waitcnt lgkmcnt(3)
	v_add_f32_e32 v4, v4, v28
	s_waitcnt lgkmcnt(2)
	v_add_f32_e32 v5, v5, v29
	s_waitcnt lgkmcnt(1)
	v_add_f32_e32 v6, v6, v30
	s_waitcnt lgkmcnt(0)
	v_add_f32_e32 v7, v7, v31
	ds_bpermute_b32 v28, v51, v4
	ds_bpermute_b32 v29, v51, v5
	ds_bpermute_b32 v30, v51, v6
	ds_bpermute_b32 v31, v51, v7
	s_waitcnt lgkmcnt(3)
	v_add_f32_e32 v4, v4, v28
	s_waitcnt lgkmcnt(2)
	v_add_f32_e32 v5, v5, v29
	s_waitcnt lgkmcnt(1)
	v_add_f32_e32 v6, v6, v30
	s_waitcnt lgkmcnt(0)
	v_add_f32_e32 v7, v7, v31
	ds_bpermute_b32 v28, v52, v4
	ds_bpermute_b32 v29, v52, v5
	ds_bpermute_b32 v30, v52, v6
	ds_bpermute_b32 v31, v52, v7
	s_waitcnt lgkmcnt(3)
	v_add_f32_e32 v4, v4, v28
	s_waitcnt lgkmcnt(2)
	v_add_f32_e32 v5, v5, v29
	s_waitcnt lgkmcnt(1)
	v_add_f32_e32 v6, v6, v30
	s_waitcnt lgkmcnt(0)
	v_add_f32_e32 v7, v7, v31
	ds_bpermute_b32 v28, v53, v4
	ds_bpermute_b32 v29, v53, v5
	ds_bpermute_b32 v30, v53, v6
	ds_bpermute_b32 v31, v53, v7
	s_waitcnt lgkmcnt(3)
	v_add_f32_e32 v4, v4, v28
	s_waitcnt lgkmcnt(2)
	v_add_f32_e32 v5, v5, v29
	s_waitcnt lgkmcnt(1)
	v_add_f32_e32 v6, v6, v30
	s_waitcnt lgkmcnt(0)
	v_add_f32_e32 v7, v7, v31
	ds_bpermute_b32 v28, v54, v4
	ds_bpermute_b32 v29, v54, v5
	ds_bpermute_b32 v30, v54, v6
	ds_bpermute_b32 v31, v54, v7
	s_waitcnt lgkmcnt(3)
	v_add_f32_e32 v4, v4, v28
	s_waitcnt lgkmcnt(2)
	v_add_f32_e32 v5, v5, v29
	s_waitcnt lgkmcnt(1)
	v_add_f32_e32 v6, v6, v30
	s_waitcnt lgkmcnt(0)
	v_add_f32_e32 v7, v7, v31
	ds_bpermute_b32 v28, v55, v4
	ds_bpermute_b32 v29, v55, v5
	ds_bpermute_b32 v30, v55, v6
	ds_bpermute_b32 v31, v55, v7
	s_waitcnt lgkmcnt(3)
	v_add_f32_e32 v4, v4, v28
	s_waitcnt lgkmcnt(2)
	v_add_f32_e32 v5, v5, v29
	s_waitcnt lgkmcnt(1)
	v_add_f32_e32 v6, v6, v30
	s_waitcnt lgkmcnt(0)
	v_add_f32_e32 v7, v7, v31
	v_fmamk_f32 v4, v4, 0x3a800000, v60
	v_fmamk_f32 v5, v5, 0x3a800000, v60
	v_fmamk_f32 v6, v6, 0x3a800000, v60
	v_fmamk_f32 v7, v7, 0x3a800000, v60
	v_rsq_f32_e32 v4, v4
	v_rsq_f32_e32 v5, v5
	v_rsq_f32_e32 v6, v6
	v_rsq_f32_e32 v7, v7
	s_nop 0
	v_lshlrev_b32_e32 v26, 16, v64
	v_and_b32_e32 v27, 0xffff0000, v64
	v_mul_f32_e32 v26, v4, v26
	v_mul_f32_e32 v27, v4, v27
	v_fma_f32 v26, v96, v26, v112
	v_fma_f32 v27, v97, v27, v113
	v_cvt_pk_bf16_f32 v32, v26, v27
	v_lshlrev_b32_e32 v26, 16, v65
	v_and_b32_e32 v27, 0xffff0000, v65
	v_mul_f32_e32 v26, v4, v26
	v_mul_f32_e32 v27, v4, v27
	v_fma_f32 v26, v98, v26, v114
	v_fma_f32 v27, v99, v27, v115
	v_cvt_pk_bf16_f32 v33, v26, v27
	v_lshlrev_b32_e32 v26, 16, v66
	v_and_b32_e32 v27, 0xffff0000, v66
	v_mul_f32_e32 v26, v4, v26
	v_mul_f32_e32 v27, v4, v27
	v_fma_f32 v26, v100, v26, v116
	v_fma_f32 v27, v101, v27, v117
	v_cvt_pk_bf16_f32 v34, v26, v27
	v_lshlrev_b32_e32 v26, 16, v67
	v_and_b32_e32 v27, 0xffff0000, v67
	v_mul_f32_e32 v26, v4, v26
	v_mul_f32_e32 v27, v4, v27
	v_fma_f32 v26, v102, v26, v118
	v_fma_f32 v27, v103, v27, v119
	v_cvt_pk_bf16_f32 v35, v26, v27
	global_store_dwordx4 v[16:17], v[32:35], off
	v_lshlrev_b32_e32 v26, 16, v68
	v_and_b32_e32 v27, 0xffff0000, v68
	v_mul_f32_e32 v26, v4, v26
	v_mul_f32_e32 v27, v4, v27
	v_fma_f32 v26, v104, v26, v40
	v_fma_f32 v27, v105, v27, v41
	v_cvt_pk_bf16_f32 v36, v26, v27
	v_lshlrev_b32_e32 v26, 16, v69
	v_and_b32_e32 v27, 0xffff0000, v69
	v_mul_f32_e32 v26, v4, v26
	v_mul_f32_e32 v27, v4, v27
	v_fma_f32 v26, v106, v26, v42
	v_fma_f32 v27, v107, v27, v43
	v_cvt_pk_bf16_f32 v37, v26, v27
	v_lshlrev_b32_e32 v26, 16, v70
	v_and_b32_e32 v27, 0xffff0000, v70
	v_mul_f32_e32 v26, v4, v26
	v_mul_f32_e32 v27, v4, v27
	v_fma_f32 v26, v108, v26, v44
	v_fma_f32 v27, v109, v27, v45
	v_cvt_pk_bf16_f32 v38, v26, v27
	v_lshlrev_b32_e32 v26, 16, v71
	v_and_b32_e32 v27, 0xffff0000, v71
	v_mul_f32_e32 v26, v4, v26
	v_mul_f32_e32 v27, v4, v27
	v_fma_f32 v26, v110, v26, v46
	v_fma_f32 v27, v111, v27, v47
	v_cvt_pk_bf16_f32 v39, v26, v27
	global_store_dwordx4 v[16:17], v[36:39], off offset:1024
	v_lshlrev_b32_e32 v26, 16, v72
	v_and_b32_e32 v27, 0xffff0000, v72
	v_mul_f32_e32 v26, v5, v26
	v_mul_f32_e32 v27, v5, v27
	v_fma_f32 v26, v96, v26, v112
	v_fma_f32 v27, v97, v27, v113
	v_cvt_pk_bf16_f32 v32, v26, v27
	v_lshlrev_b32_e32 v26, 16, v73
	v_and_b32_e32 v27, 0xffff0000, v73
	v_mul_f32_e32 v26, v5, v26
	v_mul_f32_e32 v27, v5, v27
	v_fma_f32 v26, v98, v26, v114
	v_fma_f32 v27, v99, v27, v115
	v_cvt_pk_bf16_f32 v33, v26, v27
	v_lshlrev_b32_e32 v26, 16, v74
	v_and_b32_e32 v27, 0xffff0000, v74
	v_mul_f32_e32 v26, v5, v26
	v_mul_f32_e32 v27, v5, v27
	v_fma_f32 v26, v100, v26, v116
	v_fma_f32 v27, v101, v27, v117
	v_cvt_pk_bf16_f32 v34, v26, v27
	v_lshlrev_b32_e32 v26, 16, v75
	v_and_b32_e32 v27, 0xffff0000, v75
	v_mul_f32_e32 v26, v5, v26
	v_mul_f32_e32 v27, v5, v27
	v_fma_f32 v26, v102, v26, v118
	v_fma_f32 v27, v103, v27, v119
	v_cvt_pk_bf16_f32 v35, v26, v27
	global_store_dwordx4 v[16:17], v[32:35], off offset:2048
	v_lshlrev_b32_e32 v26, 16, v76
	v_and_b32_e32 v27, 0xffff0000, v76
	v_mul_f32_e32 v26, v5, v26
	v_mul_f32_e32 v27, v5, v27
	v_fma_f32 v26, v104, v26, v40
	v_fma_f32 v27, v105, v27, v41
	v_cvt_pk_bf16_f32 v36, v26, v27
	v_lshlrev_b32_e32 v26, 16, v77
	v_and_b32_e32 v27, 0xffff0000, v77
	v_mul_f32_e32 v26, v5, v26
	v_mul_f32_e32 v27, v5, v27
	v_fma_f32 v26, v106, v26, v42
	v_fma_f32 v27, v107, v27, v43
	v_cvt_pk_bf16_f32 v37, v26, v27
	v_lshlrev_b32_e32 v26, 16, v78
	v_and_b32_e32 v27, 0xffff0000, v78
	v_mul_f32_e32 v26, v5, v26
	v_mul_f32_e32 v27, v5, v27
	v_fma_f32 v26, v108, v26, v44
	v_fma_f32 v27, v109, v27, v45
	v_cvt_pk_bf16_f32 v38, v26, v27
	v_lshlrev_b32_e32 v26, 16, v79
	v_and_b32_e32 v27, 0xffff0000, v79
	v_mul_f32_e32 v26, v5, v26
	v_mul_f32_e32 v27, v5, v27
	v_fma_f32 v26, v110, v26, v46
	v_fma_f32 v27, v111, v27, v47
	v_cvt_pk_bf16_f32 v39, v26, v27
	global_store_dwordx4 v[16:17], v[36:39], off offset:3072
	v_lshlrev_b32_e32 v26, 16, v80
	v_and_b32_e32 v27, 0xffff0000, v80
	v_mul_f32_e32 v26, v6, v26
	v_mul_f32_e32 v27, v6, v27
	v_fma_f32 v26, v96, v26, v112
	v_fma_f32 v27, v97, v27, v113
	v_cvt_pk_bf16_f32 v32, v26, v27
	v_lshlrev_b32_e32 v26, 16, v81
	v_and_b32_e32 v27, 0xffff0000, v81
	v_mul_f32_e32 v26, v6, v26
	v_mul_f32_e32 v27, v6, v27
	v_fma_f32 v26, v98, v26, v114
	v_fma_f32 v27, v99, v27, v115
	v_cvt_pk_bf16_f32 v33, v26, v27
	v_lshlrev_b32_e32 v26, 16, v82
	v_and_b32_e32 v27, 0xffff0000, v82
	v_mul_f32_e32 v26, v6, v26
	v_mul_f32_e32 v27, v6, v27
	v_fma_f32 v26, v100, v26, v116
	v_fma_f32 v27, v101, v27, v117
	v_cvt_pk_bf16_f32 v34, v26, v27
	v_lshlrev_b32_e32 v26, 16, v83
	v_and_b32_e32 v27, 0xffff0000, v83
	v_mul_f32_e32 v26, v6, v26
	v_mul_f32_e32 v27, v6, v27
	v_fma_f32 v26, v102, v26, v118
	v_fma_f32 v27, v103, v27, v119
	v_cvt_pk_bf16_f32 v35, v26, v27
	global_store_dwordx4 v[10:11], v[32:35], off
	v_lshlrev_b32_e32 v26, 16, v84
	v_and_b32_e32 v27, 0xffff0000, v84
	v_mul_f32_e32 v26, v6, v26
	v_mul_f32_e32 v27, v6, v27
	v_fma_f32 v26, v104, v26, v40
	v_fma_f32 v27, v105, v27, v41
	v_cvt_pk_bf16_f32 v36, v26, v27
	v_lshlrev_b32_e32 v26, 16, v85
	v_and_b32_e32 v27, 0xffff0000, v85
	v_mul_f32_e32 v26, v6, v26
	v_mul_f32_e32 v27, v6, v27
	v_fma_f32 v26, v106, v26, v42
	v_fma_f32 v27, v107, v27, v43
	v_cvt_pk_bf16_f32 v37, v26, v27
	v_lshlrev_b32_e32 v26, 16, v86
	v_and_b32_e32 v27, 0xffff0000, v86
	v_mul_f32_e32 v26, v6, v26
	v_mul_f32_e32 v27, v6, v27
	v_fma_f32 v26, v108, v26, v44
	v_fma_f32 v27, v109, v27, v45
	v_cvt_pk_bf16_f32 v38, v26, v27
	v_lshlrev_b32_e32 v26, 16, v87
	v_and_b32_e32 v27, 0xffff0000, v87
	v_mul_f32_e32 v26, v6, v26
	v_mul_f32_e32 v27, v6, v27
	v_fma_f32 v26, v110, v26, v46
	v_fma_f32 v27, v111, v27, v47
	v_cvt_pk_bf16_f32 v39, v26, v27
	global_store_dwordx4 v[10:11], v[36:39], off offset:1024
	v_lshlrev_b32_e32 v26, 16, v88
	v_and_b32_e32 v27, 0xffff0000, v88
	v_mul_f32_e32 v26, v7, v26
	v_mul_f32_e32 v27, v7, v27
	v_fma_f32 v26, v96, v26, v112
	v_fma_f32 v27, v97, v27, v113
	v_cvt_pk_bf16_f32 v32, v26, v27
	v_lshlrev_b32_e32 v26, 16, v89
	v_and_b32_e32 v27, 0xffff0000, v89
	v_mul_f32_e32 v26, v7, v26
	v_mul_f32_e32 v27, v7, v27
	v_fma_f32 v26, v98, v26, v114
	v_fma_f32 v27, v99, v27, v115
	v_cvt_pk_bf16_f32 v33, v26, v27
	v_lshlrev_b32_e32 v26, 16, v90
	v_and_b32_e32 v27, 0xffff0000, v90
	v_mul_f32_e32 v26, v7, v26
	v_mul_f32_e32 v27, v7, v27
	v_fma_f32 v26, v100, v26, v116
	v_fma_f32 v27, v101, v27, v117
	v_cvt_pk_bf16_f32 v34, v26, v27
	v_lshlrev_b32_e32 v26, 16, v91
	v_and_b32_e32 v27, 0xffff0000, v91
	v_mul_f32_e32 v26, v7, v26
	v_mul_f32_e32 v27, v7, v27
	v_fma_f32 v26, v102, v26, v118
	v_fma_f32 v27, v103, v27, v119
	v_cvt_pk_bf16_f32 v35, v26, v27
	global_store_dwordx4 v[10:11], v[32:35], off offset:2048
	v_lshlrev_b32_e32 v26, 16, v92
	v_and_b32_e32 v27, 0xffff0000, v92
	v_mul_f32_e32 v26, v7, v26
	v_mul_f32_e32 v27, v7, v27
	v_fma_f32 v26, v104, v26, v40
	v_fma_f32 v27, v105, v27, v41
	v_cvt_pk_bf16_f32 v36, v26, v27
	v_lshlrev_b32_e32 v26, 16, v93
	v_and_b32_e32 v27, 0xffff0000, v93
	v_mul_f32_e32 v26, v7, v26
	v_mul_f32_e32 v27, v7, v27
	v_fma_f32 v26, v106, v26, v42
	v_fma_f32 v27, v107, v27, v43
	v_cvt_pk_bf16_f32 v37, v26, v27
	v_lshlrev_b32_e32 v26, 16, v94
	v_and_b32_e32 v27, 0xffff0000, v94
	v_mul_f32_e32 v26, v7, v26
	v_mul_f32_e32 v27, v7, v27
	v_fma_f32 v26, v108, v26, v44
	v_fma_f32 v27, v109, v27, v45
	v_cvt_pk_bf16_f32 v38, v26, v27
	v_lshlrev_b32_e32 v26, 16, v95
	v_and_b32_e32 v27, 0xffff0000, v95
	v_mul_f32_e32 v26, v7, v26
	v_mul_f32_e32 v27, v7, v27
	v_fma_f32 v26, v110, v26, v46
	v_fma_f32 v27, v111, v27, v47
	v_cvt_pk_bf16_f32 v39, v26, v27
	global_store_dwordx4 v[10:11], v[36:39], off offset:3072
	s_add_i32 s35, s35, s84
	s_cmpk_gt_i32 s35, 0x1ff
	s_barrier
	s_cbranch_scc1 .LBB0_850

.LBB0_1191:
	s_or_b64 exec, exec, s[16:17]
	v_and_b32_e32 v10, 63, v0
	v_lshlrev_b32_e32 v62, 5, v10
	v_lshlrev_b32_e32 v11, 3, v10
	v_add_u32_e32 v12, s30, v1
	v_lshl_add_u32 v12, v12, 11, v11
	v_mov_b32_e32 v13, 0
	v_lshl_add_u64 v[14:15], v[12:13], 0, v[20:21]
	v_lshl_add_u64 v[16:17], v[12:13], 0, v[22:23]
	v_add_u32_e32 v12, 0x1000, v12
	v_lshl_add_u64 v[8:9], v[12:13], 0, v[20:21]
	v_lshl_add_u64 v[10:11], v[12:13], 0, v[22:23]
	global_load_dwordx4 v[64:67], v[14:15], off
	global_load_dwordx4 v[68:71], v[14:15], off offset:1024
	global_load_dwordx4 v[72:75], v[14:15], off offset:2048
	global_load_dwordx4 v[76:79], v[14:15], off offset:3072
	global_load_dwordx4 v[80:83], v[8:9], off
	global_load_dwordx4 v[84:87], v[8:9], off offset:1024
	global_load_dwordx4 v[88:91], v[8:9], off offset:2048
	global_load_dwordx4 v[92:95], v[8:9], off offset:3072
	s_waitcnt lgkmcnt(0)
	s_barrier
	ds_read_b128 v[96:99], v62 offset:4096
	ds_read_b128 v[100:103], v62 offset:4112
	ds_read_b128 v[104:107], v62 offset:6144
	ds_read_b128 v[108:111], v62 offset:6160
	ds_read_b128 v[112:115], v62
	ds_read_b128 v[116:119], v62 offset:16
	ds_read_b128 v[40:43], v62 offset:2048
	ds_read_b128 v[44:47], v62 offset:2064
	s_waitcnt vmcnt(6)
	v_lshlrev_b32_e32 v26, 16, v64
	v_and_b32_e32 v27, 0xffff0000, v64
	v_mul_f32_e32 v4, v26, v26
	v_mul_f32_e32 v2, v27, v27
	v_lshlrev_b32_e32 v26, 16, v65
	v_and_b32_e32 v27, 0xffff0000, v65
	v_fmac_f32_e32 v4, v26, v26
	v_fmac_f32_e32 v2, v27, v27
	v_lshlrev_b32_e32 v26, 16, v66
	v_and_b32_e32 v27, 0xffff0000, v66
	v_fmac_f32_e32 v4, v26, v26
	v_fmac_f32_e32 v2, v27, v27
	v_lshlrev_b32_e32 v26, 16, v67
	v_and_b32_e32 v27, 0xffff0000, v67
	v_fmac_f32_e32 v4, v26, v26
	v_fmac_f32_e32 v2, v27, v27
	v_lshlrev_b32_e32 v26, 16, v68
	v_and_b32_e32 v27, 0xffff0000, v68
	v_fmac_f32_e32 v4, v26, v26
	v_fmac_f32_e32 v2, v27, v27
	v_lshlrev_b32_e32 v26, 16, v69
	v_and_b32_e32 v27, 0xffff0000, v69
	v_fmac_f32_e32 v4, v26, v26
	v_fmac_f32_e32 v2, v27, v27
	v_lshlrev_b32_e32 v26, 16, v70
	v_and_b32_e32 v27, 0xffff0000, v70
	v_fmac_f32_e32 v4, v26, v26
	v_fmac_f32_e32 v2, v27, v27
	v_lshlrev_b32_e32 v26, 16, v71
	v_and_b32_e32 v27, 0xffff0000, v71
	v_fmac_f32_e32 v4, v26, v26
	v_fmac_f32_e32 v2, v27, v27
	v_add_f32_e32 v4, v4, v2
	s_waitcnt vmcnt(4)
	v_lshlrev_b32_e32 v26, 16, v72
	v_and_b32_e32 v27, 0xffff0000, v72
	v_mul_f32_e32 v5, v26, v26
	v_mul_f32_e32 v3, v27, v27
	v_lshlrev_b32_e32 v26, 16, v73
	v_and_b32_e32 v27, 0xffff0000, v73
	v_fmac_f32_e32 v5, v26, v26
	v_fmac_f32_e32 v3, v27, v27
	v_lshlrev_b32_e32 v26, 16, v74
	v_and_b32_e32 v27, 0xffff0000, v74
	v_fmac_f32_e32 v5, v26, v26
	v_fmac_f32_e32 v3, v27, v27
	v_lshlrev_b32_e32 v26, 16, v75
	v_and_b32_e32 v27, 0xffff0000, v75
	v_fmac_f32_e32 v5, v26, v26
	v_fmac_f32_e32 v3, v27, v27
	v_lshlrev_b32_e32 v26, 16, v76
	v_and_b32_e32 v27, 0xffff0000, v76
	v_fmac_f32_e32 v5, v26, v26
	v_fmac_f32_e32 v3, v27, v27
	v_lshlrev_b32_e32 v26, 16, v77
	v_and_b32_e32 v27, 0xffff0000, v77
	v_fmac_f32_e32 v5, v26, v26
	v_fmac_f32_e32 v3, v27, v27
	v_lshlrev_b32_e32 v26, 16, v78
	v_and_b32_e32 v27, 0xffff0000, v78
	v_fmac_f32_e32 v5, v26, v26
	v_fmac_f32_e32 v3, v27, v27
	v_lshlrev_b32_e32 v26, 16, v79
	v_and_b32_e32 v27, 0xffff0000, v79
	v_fmac_f32_e32 v5, v26, v26
	v_fmac_f32_e32 v3, v27, v27
	v_add_f32_e32 v5, v5, v3
	s_waitcnt vmcnt(2)
	v_lshlrev_b32_e32 v26, 16, v80
	v_and_b32_e32 v27, 0xffff0000, v80
	v_mul_f32_e32 v6, v26, v26
	v_mul_f32_e32 v24, v27, v27
	v_lshlrev_b32_e32 v26, 16, v81
	v_and_b32_e32 v27, 0xffff0000, v81
	v_fmac_f32_e32 v6, v26, v26
	v_fmac_f32_e32 v24, v27, v27
	v_lshlrev_b32_e32 v26, 16, v82
	v_and_b32_e32 v27, 0xffff0000, v82
	v_fmac_f32_e32 v6, v26, v26
	v_fmac_f32_e32 v24, v27, v27
	v_lshlrev_b32_e32 v26, 16, v83
	v_and_b32_e32 v27, 0xffff0000, v83
	v_fmac_f32_e32 v6, v26, v26
	v_fmac_f32_e32 v24, v27, v27
	v_lshlrev_b32_e32 v26, 16, v84
	v_and_b32_e32 v27, 0xffff0000, v84
	v_fmac_f32_e32 v6, v26, v26
	v_fmac_f32_e32 v24, v27, v27
	v_lshlrev_b32_e32 v26, 16, v85
	v_and_b32_e32 v27, 0xffff0000, v85
	v_fmac_f32_e32 v6, v26, v26
	v_fmac_f32_e32 v24, v27, v27
	v_lshlrev_b32_e32 v26, 16, v86
	v_and_b32_e32 v27, 0xffff0000, v86
	v_fmac_f32_e32 v6, v26, v26
	v_fmac_f32_e32 v24, v27, v27
	v_lshlrev_b32_e32 v26, 16, v87
	v_and_b32_e32 v27, 0xffff0000, v87
	v_fmac_f32_e32 v6, v26, v26
	v_fmac_f32_e32 v24, v27, v27
	v_add_f32_e32 v6, v6, v24
	s_waitcnt vmcnt(0)
	v_lshlrev_b32_e32 v26, 16, v88
	v_and_b32_e32 v27, 0xffff0000, v88
	v_mul_f32_e32 v7, v26, v26
	v_mul_f32_e32 v25, v27, v27
	v_lshlrev_b32_e32 v26, 16, v89
	v_and_b32_e32 v27, 0xffff0000, v89
	v_fmac_f32_e32 v7, v26, v26
	v_fmac_f32_e32 v25, v27, v27
	v_lshlrev_b32_e32 v26, 16, v90
	v_and_b32_e32 v27, 0xffff0000, v90
	v_fmac_f32_e32 v7, v26, v26
	v_fmac_f32_e32 v25, v27, v27
	v_lshlrev_b32_e32 v26, 16, v91
	v_and_b32_e32 v27, 0xffff0000, v91
	v_fmac_f32_e32 v7, v26, v26
	v_fmac_f32_e32 v25, v27, v27
	v_lshlrev_b32_e32 v26, 16, v92
	v_and_b32_e32 v27, 0xffff0000, v92
	v_fmac_f32_e32 v7, v26, v26
	v_fmac_f32_e32 v25, v27, v27
	v_lshlrev_b32_e32 v26, 16, v93
	v_and_b32_e32 v27, 0xffff0000, v93
	v_fmac_f32_e32 v7, v26, v26
	v_fmac_f32_e32 v25, v27, v27
	v_lshlrev_b32_e32 v26, 16, v94
	v_and_b32_e32 v27, 0xffff0000, v94
	v_fmac_f32_e32 v7, v26, v26
	v_fmac_f32_e32 v25, v27, v27
	v_lshlrev_b32_e32 v26, 16, v95
	v_and_b32_e32 v27, 0xffff0000, v95
	v_fmac_f32_e32 v7, v26, v26
	v_fmac_f32_e32 v25, v27, v27
	v_add_f32_e32 v7, v7, v25
	ds_bpermute_b32 v28, v50, v4
	ds_bpermute_b32 v29, v50, v5
	ds_bpermute_b32 v30, v50, v6
	ds_bpermute_b32 v31, v50, v7
	s_waitcnt lgkmcnt(3)
	v_add_f32_e32 v4, v4, v28
	s_waitcnt lgkmcnt(2)
	v_add_f32_e32 v5, v5, v29
	s_waitcnt lgkmcnt(1)
	v_add_f32_e32 v6, v6, v30
	s_waitcnt lgkmcnt(0)
	v_add_f32_e32 v7, v7, v31
	ds_bpermute_b32 v28, v51, v4
	ds_bpermute_b32 v29, v51, v5
	ds_bpermute_b32 v30, v51, v6
	ds_bpermute_b32 v31, v51, v7
	s_waitcnt lgkmcnt(3)
	v_add_f32_e32 v4, v4, v28
	s_waitcnt lgkmcnt(2)
	v_add_f32_e32 v5, v5, v29
	s_waitcnt lgkmcnt(1)
	v_add_f32_e32 v6, v6, v30
	s_waitcnt lgkmcnt(0)
	v_add_f32_e32 v7, v7, v31
	ds_bpermute_b32 v28, v52, v4
	ds_bpermute_b32 v29, v52, v5
	ds_bpermute_b32 v30, v52, v6
	ds_bpermute_b32 v31, v52, v7
	s_waitcnt lgkmcnt(3)
	v_add_f32_e32 v4, v4, v28
	s_waitcnt lgkmcnt(2)
	v_add_f32_e32 v5, v5, v29
	s_waitcnt lgkmcnt(1)
	v_add_f32_e32 v6, v6, v30
	s_waitcnt lgkmcnt(0)
	v_add_f32_e32 v7, v7, v31
	ds_bpermute_b32 v28, v53, v4
	ds_bpermute_b32 v29, v53, v5
	ds_bpermute_b32 v30, v53, v6
	ds_bpermute_b32 v31, v53, v7
	s_waitcnt lgkmcnt(3)
	v_add_f32_e32 v4, v4, v28
	s_waitcnt lgkmcnt(2)
	v_add_f32_e32 v5, v5, v29
	s_waitcnt lgkmcnt(1)
	v_add_f32_e32 v6, v6, v30
	s_waitcnt lgkmcnt(0)
	v_add_f32_e32 v7, v7, v31
	ds_bpermute_b32 v28, v54, v4
	ds_bpermute_b32 v29, v54, v5
	ds_bpermute_b32 v30, v54, v6
	ds_bpermute_b32 v31, v54, v7
	s_waitcnt lgkmcnt(3)
	v_add_f32_e32 v4, v4, v28
	s_waitcnt lgkmcnt(2)
	v_add_f32_e32 v5, v5, v29
	s_waitcnt lgkmcnt(1)
	v_add_f32_e32 v6, v6, v30
	s_waitcnt lgkmcnt(0)
	v_add_f32_e32 v7, v7, v31
	ds_bpermute_b32 v28, v55, v4
	ds_bpermute_b32 v29, v55, v5
	ds_bpermute_b32 v30, v55, v6
	ds_bpermute_b32 v31, v55, v7
	s_waitcnt lgkmcnt(3)
	v_add_f32_e32 v4, v4, v28
	s_waitcnt lgkmcnt(2)
	v_add_f32_e32 v5, v5, v29
	s_waitcnt lgkmcnt(1)
	v_add_f32_e32 v6, v6, v30
	s_waitcnt lgkmcnt(0)
	v_add_f32_e32 v7, v7, v31
	v_fmamk_f32 v4, v4, 0x3a800000, v60
	v_fmamk_f32 v5, v5, 0x3a800000, v60
	v_fmamk_f32 v6, v6, 0x3a800000, v60
	v_fmamk_f32 v7, v7, 0x3a800000, v60
	v_rsq_f32_e32 v4, v4
	v_rsq_f32_e32 v5, v5
	v_rsq_f32_e32 v6, v6
	v_rsq_f32_e32 v7, v7
	s_nop 0
	v_lshlrev_b32_e32 v26, 16, v64
	v_and_b32_e32 v27, 0xffff0000, v64
	v_mul_f32_e32 v26, v4, v26
	v_mul_f32_e32 v27, v4, v27
	v_fma_f32 v26, v96, v26, v112
	v_fma_f32 v27, v97, v27, v113
	v_cvt_pk_bf16_f32 v32, v26, v27
	v_lshlrev_b32_e32 v26, 16, v65
	v_and_b32_e32 v27, 0xffff0000, v65
	v_mul_f32_e32 v26, v4, v26
	v_mul_f32_e32 v27, v4, v27
	v_fma_f32 v26, v98, v26, v114
	v_fma_f32 v27, v99, v27, v115
	v_cvt_pk_bf16_f32 v33, v26, v27
	v_lshlrev_b32_e32 v26, 16, v66
	v_and_b32_e32 v27, 0xffff0000, v66
	v_mul_f32_e32 v26, v4, v26
	v_mul_f32_e32 v27, v4, v27
	v_fma_f32 v26, v100, v26, v116
	v_fma_f32 v27, v101, v27, v117
	v_cvt_pk_bf16_f32 v34, v26, v27
	v_lshlrev_b32_e32 v26, 16, v67
	v_and_b32_e32 v27, 0xffff0000, v67
	v_mul_f32_e32 v26, v4, v26
	v_mul_f32_e32 v27, v4, v27
	v_fma_f32 v26, v102, v26, v118
	v_fma_f32 v27, v103, v27, v119
	v_cvt_pk_bf16_f32 v35, v26, v27
	global_store_dwordx4 v[16:17], v[32:35], off
	v_lshlrev_b32_e32 v26, 16, v68
	v_and_b32_e32 v27, 0xffff0000, v68
	v_mul_f32_e32 v26, v4, v26
	v_mul_f32_e32 v27, v4, v27
	v_fma_f32 v26, v104, v26, v40
	v_fma_f32 v27, v105, v27, v41
	v_cvt_pk_bf16_f32 v36, v26, v27
	v_lshlrev_b32_e32 v26, 16, v69
	v_and_b32_e32 v27, 0xffff0000, v69
	v_mul_f32_e32 v26, v4, v26
	v_mul_f32_e32 v27, v4, v27
	v_fma_f32 v26, v106, v26, v42
	v_fma_f32 v27, v107, v27, v43
	v_cvt_pk_bf16_f32 v37, v26, v27
	v_lshlrev_b32_e32 v26, 16, v70
	v_and_b32_e32 v27, 0xffff0000, v70
	v_mul_f32_e32 v26, v4, v26
	v_mul_f32_e32 v27, v4, v27
	v_fma_f32 v26, v108, v26, v44
	v_fma_f32 v27, v109, v27, v45
	v_cvt_pk_bf16_f32 v38, v26, v27
	v_lshlrev_b32_e32 v26, 16, v71
	v_and_b32_e32 v27, 0xffff0000, v71
	v_mul_f32_e32 v26, v4, v26
	v_mul_f32_e32 v27, v4, v27
	v_fma_f32 v26, v110, v26, v46
	v_fma_f32 v27, v111, v27, v47
	v_cvt_pk_bf16_f32 v39, v26, v27
	global_store_dwordx4 v[16:17], v[36:39], off offset:1024
	v_lshlrev_b32_e32 v26, 16, v72
	v_and_b32_e32 v27, 0xffff0000, v72
	v_mul_f32_e32 v26, v5, v26
	v_mul_f32_e32 v27, v5, v27
	v_fma_f32 v26, v96, v26, v112
	v_fma_f32 v27, v97, v27, v113
	v_cvt_pk_bf16_f32 v32, v26, v27
	v_lshlrev_b32_e32 v26, 16, v73
	v_and_b32_e32 v27, 0xffff0000, v73
	v_mul_f32_e32 v26, v5, v26
	v_mul_f32_e32 v27, v5, v27
	v_fma_f32 v26, v98, v26, v114
	v_fma_f32 v27, v99, v27, v115
	v_cvt_pk_bf16_f32 v33, v26, v27
	v_lshlrev_b32_e32 v26, 16, v74
	v_and_b32_e32 v27, 0xffff0000, v74
	v_mul_f32_e32 v26, v5, v26
	v_mul_f32_e32 v27, v5, v27
	v_fma_f32 v26, v100, v26, v116
	v_fma_f32 v27, v101, v27, v117
	v_cvt_pk_bf16_f32 v34, v26, v27
	v_lshlrev_b32_e32 v26, 16, v75
	v_and_b32_e32 v27, 0xffff0000, v75
	v_mul_f32_e32 v26, v5, v26
	v_mul_f32_e32 v27, v5, v27
	v_fma_f32 v26, v102, v26, v118
	v_fma_f32 v27, v103, v27, v119
	v_cvt_pk_bf16_f32 v35, v26, v27
	global_store_dwordx4 v[16:17], v[32:35], off offset:2048
	v_lshlrev_b32_e32 v26, 16, v76
	v_and_b32_e32 v27, 0xffff0000, v76
	v_mul_f32_e32 v26, v5, v26
	v_mul_f32_e32 v27, v5, v27
	v_fma_f32 v26, v104, v26, v40
	v_fma_f32 v27, v105, v27, v41
	v_cvt_pk_bf16_f32 v36, v26, v27
	v_lshlrev_b32_e32 v26, 16, v77
	v_and_b32_e32 v27, 0xffff0000, v77
	v_mul_f32_e32 v26, v5, v26
	v_mul_f32_e32 v27, v5, v27
	v_fma_f32 v26, v106, v26, v42
	v_fma_f32 v27, v107, v27, v43
	v_cvt_pk_bf16_f32 v37, v26, v27
	v_lshlrev_b32_e32 v26, 16, v78
	v_and_b32_e32 v27, 0xffff0000, v78
	v_mul_f32_e32 v26, v5, v26
	v_mul_f32_e32 v27, v5, v27
	v_fma_f32 v26, v108, v26, v44
	v_fma_f32 v27, v109, v27, v45
	v_cvt_pk_bf16_f32 v38, v26, v27
	v_lshlrev_b32_e32 v26, 16, v79
	v_and_b32_e32 v27, 0xffff0000, v79
	v_mul_f32_e32 v26, v5, v26
	v_mul_f32_e32 v27, v5, v27
	v_fma_f32 v26, v110, v26, v46
	v_fma_f32 v27, v111, v27, v47
	v_cvt_pk_bf16_f32 v39, v26, v27
	global_store_dwordx4 v[16:17], v[36:39], off offset:3072
	v_lshlrev_b32_e32 v26, 16, v80
	v_and_b32_e32 v27, 0xffff0000, v80
	v_mul_f32_e32 v26, v6, v26
	v_mul_f32_e32 v27, v6, v27
	v_fma_f32 v26, v96, v26, v112
	v_fma_f32 v27, v97, v27, v113
	v_cvt_pk_bf16_f32 v32, v26, v27
	v_lshlrev_b32_e32 v26, 16, v81
	v_and_b32_e32 v27, 0xffff0000, v81
	v_mul_f32_e32 v26, v6, v26
	v_mul_f32_e32 v27, v6, v27
	v_fma_f32 v26, v98, v26, v114
	v_fma_f32 v27, v99, v27, v115
	v_cvt_pk_bf16_f32 v33, v26, v27
	v_lshlrev_b32_e32 v26, 16, v82
	v_and_b32_e32 v27, 0xffff0000, v82
	v_mul_f32_e32 v26, v6, v26
	v_mul_f32_e32 v27, v6, v27
	v_fma_f32 v26, v100, v26, v116
	v_fma_f32 v27, v101, v27, v117
	v_cvt_pk_bf16_f32 v34, v26, v27
	v_lshlrev_b32_e32 v26, 16, v83
	v_and_b32_e32 v27, 0xffff0000, v83
	v_mul_f32_e32 v26, v6, v26
	v_mul_f32_e32 v27, v6, v27
	v_fma_f32 v26, v102, v26, v118
	v_fma_f32 v27, v103, v27, v119
	v_cvt_pk_bf16_f32 v35, v26, v27
	global_store_dwordx4 v[10:11], v[32:35], off
	v_lshlrev_b32_e32 v26, 16, v84
	v_and_b32_e32 v27, 0xffff0000, v84
	v_mul_f32_e32 v26, v6, v26
	v_mul_f32_e32 v27, v6, v27
	v_fma_f32 v26, v104, v26, v40
	v_fma_f32 v27, v105, v27, v41
	v_cvt_pk_bf16_f32 v36, v26, v27
	v_lshlrev_b32_e32 v26, 16, v85
	v_and_b32_e32 v27, 0xffff0000, v85
	v_mul_f32_e32 v26, v6, v26
	v_mul_f32_e32 v27, v6, v27
	v_fma_f32 v26, v106, v26, v42
	v_fma_f32 v27, v107, v27, v43
	v_cvt_pk_bf16_f32 v37, v26, v27
	v_lshlrev_b32_e32 v26, 16, v86
	v_and_b32_e32 v27, 0xffff0000, v86
	v_mul_f32_e32 v26, v6, v26
	v_mul_f32_e32 v27, v6, v27
	v_fma_f32 v26, v108, v26, v44
	v_fma_f32 v27, v109, v27, v45
	v_cvt_pk_bf16_f32 v38, v26, v27
	v_lshlrev_b32_e32 v26, 16, v87
	v_and_b32_e32 v27, 0xffff0000, v87
	v_mul_f32_e32 v26, v6, v26
	v_mul_f32_e32 v27, v6, v27
	v_fma_f32 v26, v110, v26, v46
	v_fma_f32 v27, v111, v27, v47
	v_cvt_pk_bf16_f32 v39, v26, v27
	global_store_dwordx4 v[10:11], v[36:39], off offset:1024
	v_lshlrev_b32_e32 v26, 16, v88
	v_and_b32_e32 v27, 0xffff0000, v88
	v_mul_f32_e32 v26, v7, v26
	v_mul_f32_e32 v27, v7, v27
	v_fma_f32 v26, v96, v26, v112
	v_fma_f32 v27, v97, v27, v113
	v_cvt_pk_bf16_f32 v32, v26, v27
	v_lshlrev_b32_e32 v26, 16, v89
	v_and_b32_e32 v27, 0xffff0000, v89
	v_mul_f32_e32 v26, v7, v26
	v_mul_f32_e32 v27, v7, v27
	v_fma_f32 v26, v98, v26, v114
	v_fma_f32 v27, v99, v27, v115
	v_cvt_pk_bf16_f32 v33, v26, v27
	v_lshlrev_b32_e32 v26, 16, v90
	v_and_b32_e32 v27, 0xffff0000, v90
	v_mul_f32_e32 v26, v7, v26
	v_mul_f32_e32 v27, v7, v27
	v_fma_f32 v26, v100, v26, v116
	v_fma_f32 v27, v101, v27, v117
	v_cvt_pk_bf16_f32 v34, v26, v27
	v_lshlrev_b32_e32 v26, 16, v91
	v_and_b32_e32 v27, 0xffff0000, v91
	v_mul_f32_e32 v26, v7, v26
	v_mul_f32_e32 v27, v7, v27
	v_fma_f32 v26, v102, v26, v118
	v_fma_f32 v27, v103, v27, v119
	v_cvt_pk_bf16_f32 v35, v26, v27
	global_store_dwordx4 v[10:11], v[32:35], off offset:2048
	v_lshlrev_b32_e32 v26, 16, v92
	v_and_b32_e32 v27, 0xffff0000, v92
	v_mul_f32_e32 v26, v7, v26
	v_mul_f32_e32 v27, v7, v27
	v_fma_f32 v26, v104, v26, v40
	v_fma_f32 v27, v105, v27, v41
	v_cvt_pk_bf16_f32 v36, v26, v27
	v_lshlrev_b32_e32 v26, 16, v93
	v_and_b32_e32 v27, 0xffff0000, v93
	v_mul_f32_e32 v26, v7, v26
	v_mul_f32_e32 v27, v7, v27
	v_fma_f32 v26, v106, v26, v42
	v_fma_f32 v27, v107, v27, v43
	v_cvt_pk_bf16_f32 v37, v26, v27
	v_lshlrev_b32_e32 v26, 16, v94
	v_and_b32_e32 v27, 0xffff0000, v94
	v_mul_f32_e32 v26, v7, v26
	v_mul_f32_e32 v27, v7, v27
	v_fma_f32 v26, v108, v26, v44
	v_fma_f32 v27, v109, v27, v45
	v_cvt_pk_bf16_f32 v38, v26, v27
	v_lshlrev_b32_e32 v26, 16, v95
	v_and_b32_e32 v27, 0xffff0000, v95
	v_mul_f32_e32 v26, v7, v26
	v_mul_f32_e32 v27, v7, v27
	v_fma_f32 v26, v110, v26, v46
	v_fma_f32 v27, v111, v27, v47
	v_cvt_pk_bf16_f32 v39, v26, v27
	global_store_dwordx4 v[10:11], v[36:39], off offset:3072
	s_add_i32 s29, s29, s84
	s_cmpk_gt_i32 s29, 0x1ff
	s_barrier
	s_cbranch_scc1 .LBB0_1207
